# v61 + sample conv (P2): token raw rows loaded in one batch, no waits on the previous token stores
# baseline (speedup 1.0000x reference)
; __device__ __forceinline__ void vt_unit(const Params& p, int unit, bfu* tile  ) {
;     const int blk = unit & 15, bh = unit >> 4, h = bh & 15, b = bh >> 4, t0 = blk * 256, tid = threadIdx.x;
;     const bfu* proj = (const bfu*)(p.ws + WS_PROJ);
;     bfu* vt = (bfu*)(p.ws + WS_VT);
; #pragma unroll
;     for (int i = 0; i < 4; ++i) {
;         const int e = tid + 512 * i, t = e >> 3, d8 = (e & 7) * 8;
;         const uint4 v = *(const uint4*)(proj + (size_t)(b * 4096 + t0 + t) * NPROJ + 2048 + h * 64 + d8);
; __device__ __forceinline__ void phase2(const Params& p, unsigned char* lds, int bid, int G) {
;     constexpr int U_CP = 0, U_CS = 32, U_VT = 1024, U_DT = 130, NU = U_CP + U_CS + U_VT + U_DT;
;     const int tid = threadIdx.x;
;     for (int u = bid; u < NU; u += G) {
;         int j = u;
;         if (j < U_VT) { vt_unit(p, j, (bfu*)lds); continue; }
;         j -= U_VT;
;         if (j < U_CP) { const int b = j >> 7, tt = j & 127; conv_run<false, 16>(p, b, b * 4096, tt * 32 + (tid >> 8) * 16, (tid & 255) * 8); continue; }
;         j -= U_CP;
;         if (j < U_CS) { conv_run<true, 4>(p, j, MP + j * 8, (tid >> 8) * 4, (tid & 255) * 8); continue; }
;         j -= U_CS;
;         { const int wt = j * 8 + (tid >> 6); if (wt < MT / 16) dt_task(p, wt); }
;     }
; }
.LBB0_236:
	s_or_b64 exec, exec, s[0:1]
	s_mov_b32 s100, 0
.Lprobe_top:
	v_readlane_b32 s0, v252, 1
	v_bfe_u32 v175, v172, 4, 2
	v_readlane_b32 s1, v252, 2
	s_cmpk_gt_i32 s2, 0x4a1
	v_lshrrev_b32_e32 v194, 6, v172
	v_and_b32_e32 v174, 15, v172
	v_lshlrev_b32_e32 v181, 3, v172
	v_lshrrev_b32_e32 v76, 3, v172
	v_lshlrev_b32_e32 v176, 4, v175
	s_waitcnt lgkmcnt(0)
	s_barrier
	s_cbranch_scc1 .LBB0_279
	s_movk_i32 s3, 0xff
	v_cmp_lt_u32_e64 s[10:11], s3, v172
	v_and_b32_e32 v0, 56, v181
	s_movk_i32 s3, 0x214
	v_add_u32_e32 v3, 0x200, v172
	v_or_b32_e32 v4, 0x400, v172
	v_add_u32_e32 v5, 0x600, v172
	v_mad_u32_u24 v1, v0, s3, 0
	v_lshrrev_b32_e32 v100, 3, v3
	v_lshrrev_b32_e32 v102, 3, v4
	v_lshrrev_b32_e32 v104, 3, v5
	v_lshl_add_u32 v99, v76, 1, v1
	v_lshl_add_u32 v101, v100, 1, v1
	v_lshl_add_u32 v103, v102, 1, v1
	v_lshl_add_u32 v105, v104, 1, v1
	v_and_b32_e32 v1, 31, v172
	v_lshlrev_b32_e32 v2, 3, v1
	v_lshl_add_u32 v108, v1, 4, 0
	v_bfe_u32 v1, v172, 3, 2
	v_lshrrev_b32_e32 v109, 5, v3
	v_lshrrev_b32_e32 v111, 5, v4
	v_lshlrev_b32_e32 v3, 1, v1
	v_lshlrev_b32_e32 v4, 3, v0
	v_and_b32_e32 v6, 8, v181
	v_add3_u32 v115, 0, v3, v4
	v_lshlrev_b32_e32 v4, 10, v1
	v_and_b32_e32 v1, 30, v172
	v_lshlrev_b32_e32 v3, 5, v6
	v_add3_u32 v116, 0, v1, v3
	v_lshlrev_b32_e32 v1, 7, v172
	v_and_b32_e32 v8, 0xf00, v1
	v_lshlrev_b32_e32 v1, 14, v194
	v_lshl_add_u32 v1, s2, 17, v1
	v_mov_b32_e32 v65, 0
	v_and_b32_e32 v77, 12, v194
	v_lshrrev_b32_e32 v106, 5, v172
	v_lshrrev_b32_e32 v113, 5, v5
	v_lshlrev_b32_e32 v68, 4, v175
	v_lshl_or_b32 v1, v174, 10, v1
	v_or_b32_e32 v67, 0xffffdf00, v194
	v_and_b32_e32 v66, 0x7f8, v181
	s_mov_b32 s5, 0
	v_cmp_ne_u32_e64 s[6:7], 0, v77
	v_cmp_lt_u32_e64 s[8:9], 4, v77
	v_add_u32_e32 v92, -5, v77
	v_or_b32_e32 v93, 1, v77
	v_add_u32_e32 v94, -4, v77
	v_or_b32_e32 v95, 2, v77
	v_add_u32_e32 v96, -3, v77
	v_or_b32_e32 v97, 3, v194
	v_add_u32_e32 v98, -2, v77
	v_mul_u32_u24_e32 v107, 0x214, v106
	v_mul_u32_u24_e32 v110, 0x214, v109
	v_mul_u32_u24_e32 v112, 0x214, v111
	v_mul_u32_u24_e32 v114, 0x214, v113
	v_lshl_or_b32 v117, v175, 6, v174
	v_mov_b32_e32 v69, v65
	v_add_u32_e32 v70, 0xf7c00000, v1
	s_lshl_b32 s3, s92, 17
	v_lshl_or_b32 v72, v174, 11, v68
	v_mov_b32_e32 v73, v65
	s_movk_i32 s33, 0x410
	v_lshlrev_b32_e32 v118, 2, v174
	s_mov_b32 s41, 0x41a00000
	s_mov_b32 s44, 0x3f2aaaab
	v_mov_b32_e32 v119, 0x3ecc95a3
	s_mov_b32 s45, 0x3f317218
	s_mov_b32 s46, 0x7f800000
	s_mov_b32 s47, 0x33800000
	s_mov_b64 s[14:15], 0x16600000
	s_mov_b64 s[16:17], 0x2000
	s_mov_b64 s[18:19], 0x4000
	s_mov_b64 s[20:21], 0x6000
	s_movk_i32 s48, 0x2000
	s_movk_i32 s49, 0x3000
	s_mov_b64 s[22:23], 0x16800000
	s_mov_b64 s[24:25], 0x9518000
	v_lshlrev_b32_e32 v74, 1, v0
	s_mov_b32 s50, 0x4301000
	v_lshlrev_b32_e32 v78, 1, v2
	s_mov_b64 s[26:27], 0x10600000
	v_lshlrev_b32_e32 v80, 1, v4
	s_mov_b64 s[28:29], 0x12600000
	v_lshlrev_b32_e32 v82, 1, v8
	v_lshlrev_b32_e32 v84, 1, v6
	s_mov_b64 s[30:31], 0x14600000
	v_mov_b32_e32 v86, 0x3f317218
	v_mov_b32_e32 v120, 0x7f800000
	v_mov_b32_e32 v121, 0x7fc00000
	v_mov_b32_e32 v122, 0xff800000
	s_mov_b32 s51, s2
	s_branch .LBB0_239

; __device__ __forceinline__ void phase2(const Params& p, unsigned char* lds, int bid, int G) {
;     ...
;     for (int u = bid; u < NU; u += G) {
;         int j = u;
;         if (j < U_VT) { vt_unit(p, j, (bfu*)lds); continue; }
;         j -= U_VT;
;         if (j < U_CP) { const int b = j >> 7, tt = j & 127; conv_run<false, 16>(p, b, b * 4096, tt * 32 + (tid >> 8) * 16, (tid & 255) * 8); continue; }
;         j -= U_CP;
;         if (j < U_CS) { conv_run<true, 4>(p, j, MP + j * 8, (tid >> 8) * 4, (tid & 255) * 8); continue; }
;         j -= U_CS;
;         { const int wt = j * 8 + (tid >> 6); if (wt < MT / 16) dt_task(p, wt); }
;     }
; }
; __device__ __forceinline__ void phase3(const Params& p, unsigned char* lds, int bid, int G) {
;     ...
;         const bool xa = (G == 256);
;         const int x = bid & 7, sl = bid >> 3;
;         const int nun = xa ? 12 : (3072 - bid + G - 1) / G;
;     ...
;         for (int i = 0; i < nun; ++i) {
.LBB0_331:
	s_or_b64 exec, exec, s[0:1]
	v_readlane_b32 s0, v252, 3
	v_readlane_b32 s42, v252, 1
	v_readlane_b32 s1, v252, 4
	v_readlane_b32 s43, v252, 2
	s_andn2_b64 vcc, exec, s[0:1]
	s_mov_b32 s3, 12
	s_waitcnt lgkmcnt(0)
	s_barrier
	s_add_u32 s100, s100, 1
	s_cmp_lt_u32 s100, 9
	s_cbranch_scc0 .Lprobe_done
	s_nop 4
	s_branch .Lprobe_top
.Lprobe_done:
	s_cbranch_vccnz .LBB0_333
	s_abs_i32 s0, s92
	v_cvt_f32_u32_e32 v0, s0
	s_sub_i32 s1, s92, s2
	s_add_i32 s3, s1, 0xbff
	s_sub_i32 s1, 0xfffff401, s1
	v_rcp_iflag_f32_e32 v0, v0
	s_xor_b32 s5, s3, s92
	s_sub_i32 s4, 0, s0
	s_max_i32 s1, s3, s1
	v_mul_f32_e32 v0, 0x4f7ffffe, v0
	v_cvt_u32_f32_e32 v0, v0
	s_ashr_i32 s3, s5, 31
	v_readfirstlane_b32 s5, v0
	s_mul_i32 s4, s4, s5
	s_mul_hi_u32 s4, s5, s4
	s_add_i32 s5, s5, s4
	s_mul_hi_u32 s4, s1, s5
	s_mul_i32 s5, s4, s0
	s_sub_i32 s1, s1, s5
	s_add_i32 s6, s4, 1
	s_sub_i32 s5, s1, s0
	s_cmp_ge_u32 s1, s0
	s_cselect_b32 s4, s6, s4
	s_cselect_b32 s1, s5, s1
	s_add_i32 s5, s4, 1
	s_cmp_ge_u32 s1, s0
	s_cselect_b32 s0, s5, s4
	s_xor_b32 s0, s0, s3
	s_sub_i32 s3, s0, s3

; __global__ void __launch_bounds__(512) fwd_kernel(Params p_unused) {
;     extern __shared__ __attribute__((aligned(16))) unsigned char smem[];
	.amdhsa_kernel _Z10fwd_kernel6Params
		.amdhsa_group_segment_fixed_size 0
		.amdhsa_private_segment_fixed_size 0
		.amdhsa_kernarg_size 448
		.amdhsa_user_sgpr_count 2
		.amdhsa_user_sgpr_dispatch_ptr 0
		.amdhsa_user_sgpr_queue_ptr 0
		.amdhsa_user_sgpr_kernarg_segment_ptr 1
		.amdhsa_user_sgpr_dispatch_id 0
		.amdhsa_user_sgpr_kernarg_preload_length 0
		.amdhsa_user_sgpr_kernarg_preload_offset 0
		.amdhsa_user_sgpr_private_segment_size 0
		.amdhsa_uses_dynamic_stack 0
		.amdhsa_enable_private_segment 0
		.amdhsa_system_sgpr_workgroup_id_x 1
		.amdhsa_system_sgpr_workgroup_id_y 0
		.amdhsa_system_sgpr_workgroup_id_z 0
		.amdhsa_system_sgpr_workgroup_info 0
		.amdhsa_system_vgpr_workitem_id 2
		.amdhsa_next_free_vgpr 256
		.amdhsa_next_free_sgpr 102
		.amdhsa_accum_offset 256
		.amdhsa_reserve_vcc 1
		.amdhsa_float_round_mode_32 0
		.amdhsa_float_round_mode_16_64 0
		.amdhsa_float_denorm_mode_32 3
		.amdhsa_float_denorm_mode_16_64 3
		.amdhsa_dx10_clamp 1
		.amdhsa_ieee_mode 1
		.amdhsa_fp16_overflow 0
		.amdhsa_tg_split 0
		.amdhsa_exception_fp_ieee_invalid_op 0
		.amdhsa_exception_fp_denorm_src 0
		.amdhsa_exception_fp_ieee_div_zero 0
		.amdhsa_exception_fp_ieee_overflow 0
		.amdhsa_exception_fp_ieee_underflow 0
		.amdhsa_exception_fp_ieee_inexact 0
		.amdhsa_exception_int_div_zero 0
	.end_amdhsa_kernel

; __global__ void __launch_bounds__(512) fwd_kernel(Params p_unused) {
;     extern __shared__ __attribute__((aligned(16))) unsigned char smem[];
amdhsa.kernels:
  - .agpr_count:     0
    .args:
      - .offset:         0
        .size:           192
        .value_kind:     by_value
      - .offset:         192
        .size:           4
        .value_kind:     hidden_block_count_x
      - .offset:         196
        .size:           4
        .value_kind:     hidden_block_count_y
      - .offset:         200
        .size:           4
        .value_kind:     hidden_block_count_z
      - .offset:         204
        .size:           2
        .value_kind:     hidden_group_size_x
      - .offset:         206
        .size:           2
        .value_kind:     hidden_group_size_y
      - .offset:         208
        .size:           2
        .value_kind:     hidden_group_size_z
      - .offset:         210
        .size:           2
        .value_kind:     hidden_remainder_x
      - .offset:         212
        .size:           2
        .value_kind:     hidden_remainder_y
      - .offset:         214
        .size:           2
        .value_kind:     hidden_remainder_z
      - .offset:         232
        .size:           8
        .value_kind:     hidden_global_offset_x
      - .offset:         240
        .size:           8
        .value_kind:     hidden_global_offset_y
      - .offset:         248
        .size:           8
        .value_kind:     hidden_global_offset_z
      - .offset:         256
        .size:           2
        .value_kind:     hidden_grid_dims
      - .offset:         280
        .size:           8
        .value_kind:     hidden_multigrid_sync_arg
      - .offset:         312
        .size:           4
        .value_kind:     hidden_dynamic_lds_size
    .group_segment_fixed_size: 0
    .kernarg_segment_align: 8
    .kernarg_segment_size: 448
    .language:       OpenCL C
    .language_version:
      - 2
      - 0
    .max_flat_workgroup_size: 512
    .name:           _Z10fwd_kernel6Params
    .private_segment_fixed_size: 0
    .sgpr_count:     108
    .sgpr_spill_count: 22
    .symbol:         _Z10fwd_kernel6Params.kd
    .uniform_work_group_size: 1
    .uses_dynamic_stack: false
    .vgpr_count:     256
    .vgpr_spill_count: 0
    .wavefront_size: 64
